# row phases: the two bf16 streams that are read once (residual copy, branch output) use streaming (nt) loads
# speedup vs baseline: 1.0011x; 1.0011x over previous
.LBB0_510:
	s_xor_b64 s[8:9], s[18:19], -1
	v_ashrrev_i32_e32 v0, 6, v0
	v_mov_b32_e32 v112, v113
	v_mov_b32_e32 v72, v113
	v_mov_b32_e32 v73, v113
	v_mov_b32_e32 v74, v113
	v_mov_b32_e32 v75, v113
	s_waitcnt lgkmcnt(0)
	s_add_u32 s0, s50, 0x3f00000
	v_lshl_add_u32 v132, s10, 3, v0
	s_movk_i32 s4, 0x4080
	v_mov_b32_e32 v114, v113
	v_mov_b32_e32 v115, v113
	v_cndmask_b32_e64 v0, 0, 1, s[8:9]
	v_mov_b64_e32 v[86:87], v[74:75]
	v_mov_b64_e32 v[56:57], v[72:73]
	v_mov_b64_e32 v[52:53], v[72:73]
	v_mov_b64_e32 v[44:45], v[112:113]
	v_mov_b64_e32 v[40:41], v[112:113]
	v_mov_b64_e32 v[92:93], v[112:113]
	v_mov_b64_e32 v[88:89], v[112:113]
	s_addc_u32 s1, s51, 0
	v_cmp_gt_i32_e64 s[44:45], s4, v132
	v_cmp_ne_u32_e64 s[42:43], 1, v0
	v_mov_b64_e32 v[84:85], v[72:73]
	v_mov_b64_e32 v[58:59], v[74:75]
	v_mov_b64_e32 v[54:55], v[74:75]
	v_mov_b64_e32 v[46:47], v[114:115]
	v_mov_b64_e32 v[42:43], v[114:115]
	v_mov_b64_e32 v[94:95], v[114:115]
	v_mov_b64_e32 v[90:91], v[114:115]
	s_and_saveexec_b64 s[4:5], s[44:45]
	s_cbranch_execz .LBB0_518
	s_mov_b64 s[6:7], -1
	s_and_b64 vcc, exec, s[42:43]
	v_ashrrev_i32_e32 v133, 31, v132
	s_cbranch_vccnz .LBB0_513
	v_lshlrev_b64 v[0:1], 11, v[132:133]
	v_lshl_add_u64 v[0:1], s[0:1], 0, v[0:1]
	v_lshlrev_b32_e32 v112, 1, v32
	v_lshl_add_u64 v[0:1], v[0:1], 0, v[112:113]
	global_load_dwordx4 v[56:59], v[0:1], off nt
	global_load_dwordx4 v[52:55], v[0:1], off offset:1024 nt
	s_mov_b64 s[6:7], 0

.LBB0_517:
	v_lshlrev_b64 v[0:1], 11, v[132:133]
	v_lshl_add_u64 v[0:1], s[14:15], 0, v[0:1]
	v_lshlrev_b32_e32 v112, 1, v32
	v_lshl_add_u64 v[0:1], v[0:1], 0, v[112:113]
	global_load_dwordx4 v[72:75], v[0:1], off nt
	global_load_dwordx4 v[84:87], v[0:1], off offset:1024 nt
.LBB0_518:
	s_or_b64 exec, exec, s[4:5]
	s_lshl_b32 s12, s13, 3
	v_mov_b32_e32 v112, v113
	v_mov_b32_e32 v24, v113
	v_mov_b32_e32 v25, v113
	v_mov_b32_e32 v26, v113
	v_mov_b32_e32 v27, v113
	v_add_u32_e32 v36, s12, v132
	s_movk_i32 s4, 0x4080
	v_mov_b32_e32 v114, v113
	v_mov_b32_e32 v115, v113
	v_mov_b64_e32 v[30:31], v[26:27]
	v_mov_b64_e32 v[8:9], v[24:25]
	v_mov_b64_e32 v[12:13], v[24:25]
	v_mov_b64_e32 v[4:5], v[112:113]
	v_mov_b64_e32 v[0:1], v[112:113]
	v_mov_b64_e32 v[20:21], v[112:113]
	v_mov_b64_e32 v[16:17], v[112:113]
	v_cmp_gt_i32_e32 vcc, s4, v36
	v_mov_b64_e32 v[28:29], v[24:25]
	v_mov_b64_e32 v[10:11], v[26:27]
	v_mov_b64_e32 v[14:15], v[26:27]
	v_mov_b64_e32 v[6:7], v[114:115]
	v_mov_b64_e32 v[2:3], v[114:115]
	v_mov_b64_e32 v[22:23], v[114:115]
	v_mov_b64_e32 v[18:19], v[114:115]
	s_and_saveexec_b64 s[4:5], vcc
	s_cbranch_execz .LBB0_524
	s_mov_b64 s[6:7], -1
	s_and_b64 vcc, exec, s[42:43]
	v_ashrrev_i32_e32 v37, 31, v36
	s_cbranch_vccnz .LBB0_521
	v_lshlrev_b64 v[0:1], 11, v[36:37]
	v_lshl_add_u64 v[0:1], s[0:1], 0, v[0:1]
	v_lshlrev_b32_e32 v112, 1, v32
	v_lshl_add_u64 v[0:1], v[0:1], 0, v[112:113]
	global_load_dwordx4 v[8:11], v[0:1], off nt
	global_load_dwordx4 v[12:15], v[0:1], off offset:1024 nt
	s_mov_b64 s[6:7], 0

.LBB0_535:
	s_waitcnt vmcnt(1)
	v_add_u32_e32 v88, s6, v132
	s_movk_i32 s0, 0x4080
	v_mov_b64_e32 v[78:79], v[26:27]
	s_waitcnt vmcnt(0)
	v_mov_b64_e32 v[82:83], v[30:31]
	v_mov_b64_e32 v[50:51], v[10:11]
	v_mov_b64_e32 v[62:63], v[14:15]
	v_mov_b64_e32 v[54:55], v[6:7]
	v_mov_b64_e32 v[58:59], v[2:3]
	v_mov_b64_e32 v[66:67], v[22:23]
	v_mov_b64_e32 v[70:71], v[18:19]
	v_cmp_gt_i32_e32 vcc, s0, v88
	v_mov_b64_e32 v[76:77], v[24:25]
	v_mov_b64_e32 v[80:81], v[28:29]
	v_mov_b64_e32 v[48:49], v[8:9]
	v_mov_b64_e32 v[60:61], v[12:13]
	v_mov_b64_e32 v[52:53], v[4:5]
	v_mov_b64_e32 v[56:57], v[0:1]
	v_mov_b64_e32 v[64:65], v[20:21]
	v_mov_b64_e32 v[68:69], v[16:17]
	s_and_saveexec_b64 s[0:1], vcc
	s_cbranch_execz .LBB0_542
	s_mov_b64 s[4:5], -1
	s_and_b64 vcc, exec, s[42:43]
	v_ashrrev_i32_e32 v89, 31, v88
	s_cbranch_vccnz .LBB0_538
	v_lshlrev_b64 v[48:49], 11, v[88:89]
	v_lshl_add_u64 v[52:53], v[114:115], 0, v[48:49]
	global_load_dwordx4 v[48:51], v[52:53], off nt
	global_load_dwordx4 v[60:63], v[52:53], off offset:1024 nt
	s_mov_b64 s[4:5], 0

.LBB0_540:
	v_mov_b64_e32 v[78:79], v[26:27]
	v_mov_b64_e32 v[82:83], v[30:31]
	s_and_b64 vcc, exec, s[38:39]
	v_mov_b64_e32 v[76:77], v[24:25]
	v_mov_b64_e32 v[80:81], v[28:29]
	s_cbranch_vccnz .LBB0_542
	v_lshlrev_b64 v[76:77], 11, v[88:89]
	v_lshl_add_u64 v[80:81], v[134:135], 0, v[76:77]
	global_load_dwordx4 v[76:79], v[80:81], off nt
	s_nop 0
	global_load_dwordx4 v[80:83], v[80:81], off offset:1024 nt

.LBB0_556:
	v_lshlrev_b64 v[24:25], 11, v[36:37]
	v_lshl_add_u64 v[24:25], s[14:15], 0, v[24:25]
	v_lshlrev_b32_e32 v112, 1, v32
	v_lshl_add_u64 v[28:29], v[24:25], 0, v[112:113]
	global_load_dwordx4 v[24:27], v[28:29], off nt
	s_nop 0
	global_load_dwordx4 v[28:31], v[28:29], off offset:1024 nt
	s_or_b64 exec, exec, s[4:5]
	s_and_saveexec_b64 s[10:11], s[44:45]
	s_cbranch_execnz .LBB0_525
